# s32 = s29 + dma_saddr_p3 + setprio_none
# baseline (speedup 1.0000x reference)
.LBB0_425:
	s_add_u32 s12, s30, s38
	s_addc_u32 s42, s31, s39
	s_add_u32 s12, s12, 0xfff80080
	s_addc_u32 s65, s42, -1
	s_cmp_eq_u32 s64, 30
	s_cselect_b64 s[42:43], -1, 0
	s_and_b64 s[42:43], s[42:43], exec
	s_cselect_b32 s43, s19, s65
	s_cselect_b32 s42, s21, s12
	s_add_i32 s65, s64, 2
	s_cmp_eq_u32 s64, 30
	s_cselect_b64 s[66:67], -1, 0
	s_and_b64 s[68:69], s[66:67], exec
	s_cselect_b32 s12, 0, s65
	s_and_b64 s[66:67], s[66:67], s[4:5]
	s_and_b64 s[66:67], s[66:67], exec
	s_cselect_b32 s68, s23, s35
	s_cselect_b32 s69, s22, s34
	s_cselect_b32 s66, s27, s37
	s_cselect_b32 s67, s26, s36
	v_lshl_add_u64 v[214:215], s[44:45], 0, v[214:215]
	s_add_i32 m0, s29, 0xc000
	v_lshl_add_u64 v[2:3], s[44:45], 0, v[2:3]
	global_load_lds_dwordx4 v[214:215], off
	s_add_i32 m0, s29, 0xe000
	s_nop 0
	global_load_lds_dwordx4 v[2:3], off
	s_waitcnt vmcnt(8)
	s_waitcnt lgkmcnt(0)
	s_barrier
	v_mfma_f32_16x16x32_bf16 v[128:131], v[148:151], v[188:191], v[128:131]
	v_mfma_f32_16x16x32_bf16 v[124:127], v[156:159], v[188:191], v[124:127]
	v_mfma_f32_16x16x32_bf16 v[112:115], v[148:151], v[180:183], v[112:115]
	v_mfma_f32_16x16x32_bf16 v[108:111], v[156:159], v[180:183], v[108:111]
	v_mfma_f32_16x16x32_bf16 v[96:99], v[148:151], v[172:175], v[96:99]
	v_mfma_f32_16x16x32_bf16 v[92:95], v[156:159], v[172:175], v[92:95]
	v_mfma_f32_16x16x32_bf16 v[80:83], v[148:151], v[164:167], v[80:83]
	v_mfma_f32_16x16x32_bf16 v[76:79], v[156:159], v[164:167], v[76:79]
	v_mfma_f32_16x16x32_bf16 v[128:131], v[152:155], v[192:195], v[128:131]
	v_mfma_f32_16x16x32_bf16 v[124:127], v[160:163], v[192:195], v[124:127]
	v_mfma_f32_16x16x32_bf16 v[112:115], v[152:155], v[184:187], v[112:115]
	v_mfma_f32_16x16x32_bf16 v[108:111], v[160:163], v[184:187], v[108:111]
	v_mfma_f32_16x16x32_bf16 v[96:99], v[152:155], v[176:179], v[96:99]
	v_mfma_f32_16x16x32_bf16 v[92:95], v[160:163], v[176:179], v[92:95]
	v_mfma_f32_16x16x32_bf16 v[80:83], v[152:155], v[168:171], v[80:83]
	v_mfma_f32_16x16x32_bf16 v[76:79], v[160:163], v[168:171], v[76:79]
	v_mfma_f32_16x16x32_bf16 v[120:123], v[132:135], v[188:191], v[120:123]
	v_mfma_f32_16x16x32_bf16 v[116:119], v[140:143], v[188:191], v[116:119]
	v_mfma_f32_16x16x32_bf16 v[104:107], v[132:135], v[180:183], v[104:107]
	v_mfma_f32_16x16x32_bf16 v[100:103], v[140:143], v[180:183], v[100:103]
	v_mfma_f32_16x16x32_bf16 v[88:91], v[132:135], v[172:175], v[88:91]
	v_mfma_f32_16x16x32_bf16 v[84:87], v[140:143], v[172:175], v[84:87]
	v_mfma_f32_16x16x32_bf16 v[72:75], v[132:135], v[164:167], v[72:75]
	v_mfma_f32_16x16x32_bf16 v[68:71], v[140:143], v[164:167], v[68:71]
	v_mfma_f32_16x16x32_bf16 v[120:123], v[136:139], v[192:195], v[120:123]
	v_mfma_f32_16x16x32_bf16 v[116:119], v[144:147], v[192:195], v[116:119]
	v_mfma_f32_16x16x32_bf16 v[104:107], v[136:139], v[184:187], v[104:107]
	v_mfma_f32_16x16x32_bf16 v[100:103], v[144:147], v[184:187], v[100:103]
	v_mfma_f32_16x16x32_bf16 v[88:91], v[136:139], v[176:179], v[88:91]
	v_mfma_f32_16x16x32_bf16 v[84:87], v[144:147], v[176:179], v[84:87]
	v_mfma_f32_16x16x32_bf16 v[72:75], v[136:139], v[168:171], v[72:75]
	v_mfma_f32_16x16x32_bf16 v[68:71], v[144:147], v[168:171], v[68:71]
	s_barrier
	s_mov_b32 m0, s47
	v_lshl_add_u64 v[214:215], s[42:43], 0, v[198:199]
	s_add_u32 s44, s42, 0x80000
	ds_read_b128 v[164:167], v219 offset:16384
	ds_read_b128 v[168:171], v219 offset:17408
	ds_read_b128 v[172:175], v219 offset:18432
	ds_read_b128 v[176:179], v219 offset:19456
	ds_read_b128 v[180:183], v219 offset:20480
	ds_read_b128 v[184:187], v219 offset:21504
	ds_read_b128 v[188:191], v219 offset:22528
	ds_read_b128 v[192:195], v219 offset:23552
	global_load_lds_dwordx4 v[214:215], off
	v_lshl_add_u64 v[220:221], s[42:43], 0, v[202:203]
	s_mov_b32 m0, s48
	s_addc_u32 s45, s43, 0
	global_load_lds_dwordx4 v[220:221], off
	s_mov_b32 m0, s49
	s_add_i32 s70, s12, -8
	global_load_lds_dwordx4 v198, s[44:45]
	v_lshl_add_u64 v[2:3], s[44:45], 0, v[202:203]
	s_lshl_b64 s[44:45], s[12:13], 7
	s_add_u32 s71, s69, s44
	s_addc_u32 s72, s68, s45
	s_lshl_b32 s44, s70, 19
	s_add_u32 s73, s67, s44
	s_addc_u32 s74, s66, 0
	s_add_i32 s75, 0, 0x18000
	s_add_i32 s76, 0, 0x1c000
	s_add_u32 s77, s71, 0x80000
	s_addc_u32 s84, s72, 0
	s_add_u32 s85, s73, 0x800
	s_addc_u32 s86, s74, 0
	s_cmp_lt_u32 s70, 16
	s_cselect_b64 vcc, -1, 0
	s_and_b64 s[44:45], vcc, exec
	s_mov_b32 m0, s50
	v_cndmask_b32_e32 v222, v196, v204, vcc
	v_mov_b32_e32 v223, v1
	s_cselect_b32 s45, s74, s72
	s_cselect_b32 s44, s73, s71
	global_load_lds_dwordx4 v[2:3], off
	v_cndmask_b32_e32 v0, v200, v206, vcc
	s_mov_b32 m0, s29
	s_nop 0
	global_load_lds_dwordx4 v222, s[44:45]
	s_mov_b32 m0, s51
	s_nop 0
	global_load_lds_dwordx4 v0, s[44:45]
	s_waitcnt vmcnt(8)
	s_waitcnt lgkmcnt(0)
	s_barrier
	v_mfma_f32_16x16x32_bf16 v[64:67], v[148:151], v[164:167], v[64:67]
	v_mfma_f32_16x16x32_bf16 v[60:63], v[156:159], v[164:167], v[60:63]
	v_mfma_f32_16x16x32_bf16 v[48:51], v[148:151], v[172:175], v[48:51]
	v_mfma_f32_16x16x32_bf16 v[44:47], v[156:159], v[172:175], v[44:47]
	v_mfma_f32_16x16x32_bf16 v[32:35], v[148:151], v[180:183], v[32:35]
	v_mfma_f32_16x16x32_bf16 v[28:31], v[156:159], v[180:183], v[28:31]
	v_mfma_f32_16x16x32_bf16 v[16:19], v[148:151], v[188:191], v[16:19]
	v_mfma_f32_16x16x32_bf16 v[12:15], v[156:159], v[188:191], v[12:15]
	v_mfma_f32_16x16x32_bf16 v[64:67], v[152:155], v[168:171], v[64:67]
	v_mfma_f32_16x16x32_bf16 v[60:63], v[160:163], v[168:171], v[60:63]
	v_mfma_f32_16x16x32_bf16 v[48:51], v[152:155], v[176:179], v[48:51]
	v_mfma_f32_16x16x32_bf16 v[44:47], v[160:163], v[176:179], v[44:47]
	v_mfma_f32_16x16x32_bf16 v[32:35], v[152:155], v[184:187], v[32:35]
	v_mfma_f32_16x16x32_bf16 v[28:31], v[160:163], v[184:187], v[28:31]
	v_mfma_f32_16x16x32_bf16 v[16:19], v[152:155], v[192:195], v[16:19]
	v_mfma_f32_16x16x32_bf16 v[12:15], v[160:163], v[192:195], v[12:15]
	v_mfma_f32_16x16x32_bf16 v[56:59], v[132:135], v[164:167], v[56:59]
	v_mfma_f32_16x16x32_bf16 v[52:55], v[140:143], v[164:167], v[52:55]
	v_mfma_f32_16x16x32_bf16 v[40:43], v[132:135], v[172:175], v[40:43]
	v_mfma_f32_16x16x32_bf16 v[36:39], v[140:143], v[172:175], v[36:39]
	v_mfma_f32_16x16x32_bf16 v[24:27], v[132:135], v[180:183], v[24:27]
	v_mfma_f32_16x16x32_bf16 v[20:23], v[140:143], v[180:183], v[20:23]
	v_mfma_f32_16x16x32_bf16 v[8:11], v[132:135], v[188:191], v[8:11]
	v_mfma_f32_16x16x32_bf16 v[2:5], v[140:143], v[188:191], v[4:7]
	v_mfma_f32_16x16x32_bf16 v[56:59], v[136:139], v[168:171], v[56:59]
	v_mfma_f32_16x16x32_bf16 v[52:55], v[144:147], v[168:171], v[52:55]
	v_mfma_f32_16x16x32_bf16 v[40:43], v[136:139], v[176:179], v[40:43]
	v_mfma_f32_16x16x32_bf16 v[36:39], v[144:147], v[176:179], v[36:39]
	v_mfma_f32_16x16x32_bf16 v[24:27], v[136:139], v[184:187], v[24:27]
	v_mfma_f32_16x16x32_bf16 v[20:23], v[144:147], v[184:187], v[20:23]
	v_mfma_f32_16x16x32_bf16 v[8:11], v[136:139], v[192:195], v[8:11]
	v_mfma_f32_16x16x32_bf16 v[2:5], v[144:147], v[192:195], v[2:5]
	s_barrier
	v_add_u32_e32 v6, s75, v217
	ds_read_b128 v[148:151], v6
	ds_read_b128 v[152:155], v6 offset:1024
	ds_read_b128 v[156:159], v6 offset:2048
	ds_read_b128 v[160:163], v6 offset:3072
	v_add_u32_e32 v6, s76, v217
	ds_read_b128 v[132:135], v6
	ds_read_b128 v[136:139], v6 offset:1024
	ds_read_b128 v[140:143], v6 offset:2048
	ds_read_b128 v[144:147], v6 offset:3072
	s_cselect_b32 s45, s86, s84
	s_cselect_b32 s44, s85, s77
	s_mov_b32 m0, s52
	ds_read_b128 v[164:167], v219 offset:32768
	ds_read_b128 v[168:171], v219 offset:33792
	ds_read_b128 v[172:175], v219 offset:34816
	ds_read_b128 v[176:179], v219 offset:35840
	ds_read_b128 v[180:183], v219 offset:36864
	ds_read_b128 v[184:187], v219 offset:37888
	ds_read_b128 v[188:191], v219 offset:38912
	ds_read_b128 v[192:195], v219 offset:39936
	global_load_lds_dwordx4 v222, s[44:45]
	s_mov_b32 m0, s53
	s_nop 0
	global_load_lds_dwordx4 v0, s[44:45]
	s_waitcnt vmcnt(8)
	s_waitcnt lgkmcnt(0)
	s_barrier
	v_mfma_f32_16x16x32_bf16 v[128:131], v[148:151], v[164:167], v[128:131]
	v_mfma_f32_16x16x32_bf16 v[124:127], v[156:159], v[164:167], v[124:127]
	v_mfma_f32_16x16x32_bf16 v[112:115], v[148:151], v[172:175], v[112:115]
	v_mfma_f32_16x16x32_bf16 v[108:111], v[156:159], v[172:175], v[108:111]
	v_mfma_f32_16x16x32_bf16 v[96:99], v[148:151], v[180:183], v[96:99]
	v_mfma_f32_16x16x32_bf16 v[92:95], v[156:159], v[180:183], v[92:95]
	v_mfma_f32_16x16x32_bf16 v[80:83], v[148:151], v[188:191], v[80:83]
	v_mfma_f32_16x16x32_bf16 v[76:79], v[156:159], v[188:191], v[76:79]
	v_mfma_f32_16x16x32_bf16 v[128:131], v[152:155], v[168:171], v[128:131]
	v_mfma_f32_16x16x32_bf16 v[124:127], v[160:163], v[168:171], v[124:127]
	v_mfma_f32_16x16x32_bf16 v[112:115], v[152:155], v[176:179], v[112:115]
	v_mfma_f32_16x16x32_bf16 v[108:111], v[160:163], v[176:179], v[108:111]
	v_mfma_f32_16x16x32_bf16 v[96:99], v[152:155], v[184:187], v[96:99]
	v_mfma_f32_16x16x32_bf16 v[92:95], v[160:163], v[184:187], v[92:95]
	v_mfma_f32_16x16x32_bf16 v[80:83], v[152:155], v[192:195], v[80:83]
	v_mfma_f32_16x16x32_bf16 v[76:79], v[160:163], v[192:195], v[76:79]
	v_mfma_f32_16x16x32_bf16 v[120:123], v[132:135], v[164:167], v[120:123]
	v_mfma_f32_16x16x32_bf16 v[116:119], v[140:143], v[164:167], v[116:119]
	v_mfma_f32_16x16x32_bf16 v[104:107], v[132:135], v[172:175], v[104:107]
	v_mfma_f32_16x16x32_bf16 v[100:103], v[140:143], v[172:175], v[100:103]
	v_mfma_f32_16x16x32_bf16 v[88:91], v[132:135], v[180:183], v[88:91]
	v_mfma_f32_16x16x32_bf16 v[84:87], v[140:143], v[180:183], v[84:87]
	v_mfma_f32_16x16x32_bf16 v[72:75], v[132:135], v[188:191], v[72:75]
	v_mfma_f32_16x16x32_bf16 v[68:71], v[140:143], v[188:191], v[68:71]
	v_mfma_f32_16x16x32_bf16 v[120:123], v[136:139], v[168:171], v[120:123]
	v_mfma_f32_16x16x32_bf16 v[116:119], v[144:147], v[168:171], v[116:119]
	v_mfma_f32_16x16x32_bf16 v[104:107], v[136:139], v[176:179], v[104:107]
	v_mfma_f32_16x16x32_bf16 v[100:103], v[144:147], v[176:179], v[100:103]
	v_mfma_f32_16x16x32_bf16 v[88:91], v[136:139], v[184:187], v[88:91]
	v_mfma_f32_16x16x32_bf16 v[84:87], v[144:147], v[184:187], v[84:87]
	v_mfma_f32_16x16x32_bf16 v[72:75], v[136:139], v[192:195], v[72:75]
	v_mfma_f32_16x16x32_bf16 v[68:71], v[144:147], v[192:195], v[68:71]
	s_barrier
	s_add_i32 s44, s75, s33
	v_lshl_add_u64 v[6:7], v[214:215], 0, s[14:15]
	s_mov_b32 m0, s44
	ds_read_b128 v[188:191], v219 offset:49152
	ds_read_b128 v[192:195], v219 offset:50176
	ds_read_b128 v[180:183], v219 offset:51200
	ds_read_b128 v[184:187], v219 offset:52224
	ds_read_b128 v[172:175], v219 offset:53248
	ds_read_b128 v[176:179], v219 offset:54272
	ds_read_b128 v[164:167], v219 offset:55296
	ds_read_b128 v[168:171], v219 offset:56320
	global_load_lds_dwordx4 v[6:7], off
	s_add_i32 m0, s44, 0x2000
	s_add_u32 s42, s42, 0x80080
	v_lshl_add_u64 v[6:7], v[220:221], 0, s[14:15]
	s_addc_u32 s43, s43, 0
	s_add_i32 s44, s76, s33
	global_load_lds_dwordx4 v[6:7], off
	s_mov_b32 m0, s44
	s_add_i32 s70, s12, -7
	global_load_lds_dwordx4 v198, s[42:43]
	s_add_i32 m0, s44, 0x2000
	s_cmp_gt_u32 s70, 15
	global_load_lds_dwordx4 v202, s[42:43]
	s_mov_b64 s[44:45], -1
	s_cbranch_scc0 .LBB0_427
	s_or_b32 s12, s12, 1
	s_lshl_b64 s[42:43], s[12:13], 7
	s_add_u32 s42, s69, s42
	s_addc_u32 s43, s68, s43
	s_mov_b64 s[44:45], 0
